# sp3 retention-output second-round items spread over waves 0-3 of every workgroup (balances VALU load across CUs)
# speedup vs baseline: 1.0137x; 1.0137x over previous
; __device__ __forceinline__ void rot8(u32x4 x1, u32x4 x2, const float* cs, const float* sn, float sc, u32x4& o1, u32x4& o2) {
;     const f32x4 c0 = *(const f32x4*)cs, c1 = *(const f32x4*)(cs + 4), s0 = *(const f32x4*)sn, s1 = *(const f32x4*)(sn + 4);
;     float a[8], b[8], c[8], s[8];
;     a[0] = bflo(x1.x); a[1] = bfhi(x1.x); a[2] = bflo(x1.y); a[3] = bfhi(x1.y); a[4] = bflo(x1.z); a[5] = bfhi(x1.z); a[6] = bflo(x1.w); a[7] = bfhi(x1.w);
;     b[0] = bflo(x2.x); b[1] = bfhi(x2.x); b[2] = bflo(x2.y); b[3] = bfhi(x2.y); b[4] = bflo(x2.z); b[5] = bfhi(x2.z); b[6] = bflo(x2.w); b[7] = bfhi(x2.w);
; #pragma unroll
;     for (int i = 0; i < 4; ++i) { c[i] = c0[i]; c[4 + i] = c1[i]; s[i] = s0[i]; s[4 + i] = s1[i]; }
;     float p[8], q[8];
; #pragma unroll
; __device__ __forceinline__ void retout_item(const bf16_t* hbuf, const float* rot, const float* kvbuf, const float* normg, bf16_t* mixed, LAS bf16_t* vT, int item, int lane) {
;     ...
;     for (int ct = 0; ct < 4; ++ct) {
;         const int c = 16 * ct + r; const bf16_t* qp = hbuf + (t0 + c) * INWP + C_RQ + h * 64 + 8 * q; const int pos = n * 64 + c; u32x4 o1, o2;
;         rot8(*(const u32x4*)qp, *(const u32x4*)(qp + 32), cs + (size_t)pos * 32 + 8 * q, sn + (size_t)pos * 32 + 8 * q, 1.0f, o1, o2);
;         const bf16x8 q0 = as_bf16x8(o1), q1 = as_bf16x8(o2);
;         f32x4 OT[4];
;         const float xi = __builtin_amdgcn_exp2f(l2g * (float)(c + 1));
; #pragma unroll
;         for (int et = 0; et < 4; ++et) { f32x4 acc = {0.f, 0.f, 0.f, 0.f};
;             const bf16x8 R0 = *(const LAS bf16x8*)(RT + (16 * et + r) * TLD + 8 * q), R1 = *(const LAS bf16x8*)(RT + (16 * et + r) * TLD + 32 + 8 * q);
;             acc = __builtin_amdgcn_mfma_f32_16x16x32_bf16(R0, q0, acc, 0, 0, 0); acc = __builtin_amdgcn_mfma_f32_16x16x32_bf16(R1, q1, acc, 0, 0, 0);
;             OT[et] = acc * xi; }
;         f32x4 st[4];
; #pragma unroll
;         for (int mt = 0; mt < 4; ++mt) { f32x4 acc = {0.f, 0.f, 0.f, 0.f};
;             acc = __builtin_amdgcn_mfma_f32_16x16x32_bf16(kf[mt][0], q0, acc, 0, 0, 0); acc = __builtin_amdgcn_mfma_f32_16x16x32_bf16(kf[mt][1], q1, acc, 0, 0, 0);
; #pragma unroll
;             for (int j = 0; j < 4; ++j) { const int m = 16 * mt + 4 * q + j; const int dd = c > m ? c - m : m - c; acc[j] *= __builtin_amdgcn_exp2f(l2g * (float)dd); }
;             st[mt] = acc; }
.LBB0_176:
	v_add_u32_e32 v44, s12, v87
	v_lshl_add_u64 v[34:35], v[100:101], 0, s[36:37]
	v_ashrrev_i32_e32 v45, 31, v44
	v_add_co_u32_e32 v40, vcc, 0x1d408000, v34
	v_lshlrev_b64 v[44:45], 7, v[44:45]
	s_nop 0
	v_addc_co_u32_e32 v41, vcc, 0, v35, vcc
	v_lshl_add_u64 v[48:49], v[64:65], 0, v[44:45]
	v_lshl_add_u64 v[56:57], v[66:67], 0, v[44:45]
	global_load_dwordx4 v[34:37], v[40:41], off offset:2816
	s_nop 0
	global_load_dwordx4 v[40:43], v[40:41], off offset:2880
	s_nop 0
	global_load_dwordx4 v[44:47], v[48:49], off offset:16
	s_nop 0
	global_load_dwordx4 v[48:51], v[48:49], off
	s_nop 0
	global_load_dwordx4 v[52:55], v[56:57], off offset:16
	s_nop 0
	global_load_dwordx4 v[56:59], v[56:57], off
	v_add_u32_e32 v93, s12, v60
	v_cmp_gt_u32_e32 vcc, v93, v61
	v_subrev_u32_e32 v141, 19, v91
	s_mov_b64 s[20:21], 0x8000
	v_lshl_add_u64 v[100:101], v[100:101], 0, s[10:11]
	s_waitcnt vmcnt(5)
	v_lshlrev_b32_e32 v131, 16, v34
	s_waitcnt vmcnt(4)
	v_lshlrev_b32_e32 v130, 16, v40
	s_waitcnt vmcnt(0)
	v_mov_b32_e32 v132, v56
	v_mov_b32_e32 v133, v48
	v_pk_mul_f32 v[132:133], v[132:133], v[130:131]
	s_nop 0
	v_sub_f32_e32 v89, v133, v132
	v_mov_b32_e32 v132, v48
	v_mov_b32_e32 v133, v56
	v_pk_mul_f32 v[130:131], v[132:133], v[130:131]
	v_mov_b32_e32 v48, v57
	v_add_f32_e32 v95, v130, v131
	v_and_b32_e32 v131, 0xffff0000, v34
	v_and_b32_e32 v130, 0xffff0000, v40
	v_mov_b32_e32 v56, v49
	v_pk_mul_f32 v[132:133], v[48:49], v[130:131]
	v_pk_mul_f32 v[48:49], v[56:57], v[130:131]
	v_mov_b32_e32 v56, v58
	v_add_f32_e32 v130, v48, v49
	v_lshlrev_b32_e32 v49, 16, v35
	v_lshlrev_b32_e32 v48, 16, v41
	v_mov_b32_e32 v57, v50
	v_pk_mul_f32 v[56:57], v[56:57], v[48:49]
	v_and_b32_e32 v35, 0xffff0000, v35
	v_sub_f32_e32 v131, v57, v56
	v_mov_b32_e32 v56, v50
	v_mov_b32_e32 v57, v58
	v_and_b32_e32 v34, 0xffff0000, v41
	v_mov_b32_e32 v50, v59
	v_mov_b32_e32 v58, v51
	v_pk_mul_f32 v[48:49], v[56:57], v[48:49]
	v_pk_mul_f32 v[40:41], v[50:51], v[34:35]
	v_pk_mul_f32 v[34:35], v[58:59], v[34:35]
	v_add_f32_e32 v48, v48, v49
	v_sub_f32_e32 v49, v41, v40
	v_add_f32_e32 v50, v34, v35
	v_lshlrev_b32_e32 v35, 16, v36
	v_lshlrev_b32_e32 v34, 16, v42
	v_mov_b32_e32 v40, v52
	v_mov_b32_e32 v41, v44
	v_pk_mul_f32 v[40:41], v[40:41], v[34:35]
	v_sub_f32_e32 v129, v133, v132
	v_sub_f32_e32 v51, v41, v40
	v_mov_b32_e32 v40, v44
	v_mov_b32_e32 v41, v52
	v_pk_mul_f32 v[34:35], v[40:41], v[34:35]
	v_mov_b32_e32 v44, v53
	v_add_f32_e32 v56, v34, v35
	v_and_b32_e32 v35, 0xffff0000, v36
	v_and_b32_e32 v34, 0xffff0000, v42
	v_mov_b32_e32 v52, v45
	v_pk_mul_f32 v[40:41], v[44:45], v[34:35]
	v_pk_mul_f32 v[34:35], v[52:53], v[34:35]
	v_sub_f32_e32 v42, v41, v40
	v_add_f32_e32 v44, v34, v35
	v_lshlrev_b32_e32 v35, 16, v37
	v_lshlrev_b32_e32 v34, 16, v43
	v_mov_b32_e32 v40, v54
	v_mov_b32_e32 v41, v46
	v_pk_mul_f32 v[40:41], v[40:41], v[34:35]
	s_nop 0
	v_sub_f32_e32 v45, v41, v40
	v_mov_b32_e32 v40, v46
	v_mov_b32_e32 v41, v54
	v_pk_mul_f32 v[34:35], v[40:41], v[34:35]
	v_mov_b32_e32 v46, v55
	v_add_f32_e32 v52, v34, v35
	v_and_b32_e32 v35, 0xffff0000, v37
	v_and_b32_e32 v34, 0xffff0000, v43
	v_mov_b32_e32 v54, v47
	v_pk_mul_f32 v[36:37], v[46:47], v[34:35]
	v_pk_mul_f32 v[34:35], v[54:55], v[34:35]
	v_sub_f32_e32 v37, v37, v36
	v_add_f32_e32 v43, v34, v35
	v_cvt_pk_bf16_f32 v35, v131, v49
	v_cvt_pk_bf16_f32 v36, v51, v42
	v_cvt_pk_bf16_f32 v41, v48, v50
	v_cvt_pk_bf16_f32 v43, v52, v43
	ds_read_b128 v[46:49], v104 offset:9216
	ds_read_b128 v[50:53], v104 offset:9280
	v_cvt_pk_bf16_f32 v42, v56, v44
	v_add_u32_e32 v44, 1, v93
	v_cvt_f32_u32_e32 v44, v44
	v_cvt_pk_bf16_f32 v34, v89, v129
	v_cvt_pk_bf16_f32 v37, v45, v37
	v_cvt_pk_bf16_f32 v40, v95, v130
	v_mul_f32_e32 v44, v85, v44
	s_waitcnt lgkmcnt(1)
	v_mfma_f32_16x16x32_bf16 v[46:49], v[46:49], v[34:37], 0
	v_exp_f32_e32 v44, v44
	v_add_u32_e32 v129, s12, v127
	v_subrev_u32_e32 v89, 51, v91
	s_waitcnt lgkmcnt(0)
	v_mfma_f32_16x16x32_bf16 v[46:49], v[50:53], v[40:43], v[46:49]
	v_cndmask_b32_e32 v89, v89, v129, vcc
	v_cvt_f32_u32_e32 v89, v89
	v_cmp_gt_u32_e32 vcc, v93, v111
	s_add_i32 s12, s12, 16
	s_cmp_lg_u32 s12, 64
	s_nop 2
	v_pk_mul_f32 v[58:59], v[44:45], v[48:49] op_sel_hi:[0,1]
	v_pk_mul_f32 v[56:57], v[44:45], v[46:47] op_sel_hi:[0,1]
	ds_read_b128 v[46:49], v106 offset:9216
	ds_read_b128 v[50:53], v106 offset:9280
	s_waitcnt lgkmcnt(1)
	v_mfma_f32_16x16x32_bf16 v[46:49], v[46:49], v[34:37], 0
	v_mul_f32_e32 v89, v85, v89
	v_exp_f32_e32 v89, v89
	s_waitcnt lgkmcnt(0)
	v_mfma_f32_16x16x32_bf16 v[46:49], v[50:53], v[40:43], v[46:49]
	s_nop 7
	v_pk_mul_f32 v[54:55], v[44:45], v[48:49] op_sel_hi:[0,1]
	v_pk_mul_f32 v[52:53], v[44:45], v[46:47] op_sel_hi:[0,1]
	ds_read_b128 v[46:49], v108 offset:9216
	ds_read_b128 v[130:133], v108 offset:9280
	s_waitcnt lgkmcnt(1)
	v_mfma_f32_16x16x32_bf16 v[46:49], v[46:49], v[34:37], 0
	s_waitcnt lgkmcnt(0)
	v_mfma_f32_16x16x32_bf16 v[46:49], v[130:133], v[40:43], v[46:49]
	ds_read_b128 v[130:133], v110 offset:9216
	ds_read_b128 v[134:137], v110 offset:9280
	s_waitcnt lgkmcnt(1)
	v_mfma_f32_16x16x32_bf16 v[130:133], v[130:133], v[34:37], 0
	s_nop 3
	v_mul_f32_e64 v50, v44, v48
	v_mul_f32_e64 v51, v44, v49
	v_pk_mul_f32 v[48:49], v[44:45], v[46:47] op_sel_hi:[0,1]
	s_waitcnt lgkmcnt(0)
; __device__ __forceinline__ bf16x8 pack_tiles(const f32x4& t0, const f32x4& t1) { u32x4 w; w.x = pk2(t0[0], t0[1]); w.y = pk2(t0[2], t0[3]); w.z = pk2(t1[0], t1[1]); w.w = pk2(t1[2], t1[3]); return as_bf16x8(w); }
; __device__ __forceinline__ void retout_item(const bf16_t* hbuf, const float* rot, const float* kvbuf, const float* normg, bf16_t* mixed, LAS bf16_t* vT, int item, int lane) {
;     ...
;         for (int mt = 0; mt < 4; ++mt) { f32x4 acc = {0.f, 0.f, 0.f, 0.f};
;             acc = __builtin_amdgcn_mfma_f32_16x16x32_bf16(kf[mt][0], q0, acc, 0, 0, 0); acc = __builtin_amdgcn_mfma_f32_16x16x32_bf16(kf[mt][1], q1, acc, 0, 0, 0);
; #pragma unroll
;             for (int j = 0; j < 4; ++j) { const int m = 16 * mt + 4 * q + j; const int dd = c > m ? c - m : m - c; acc[j] *= __builtin_amdgcn_exp2f(l2g * (float)dd); }
;             st[mt] = acc; }
;         const bf16x8 p0 = pack_tiles(st[0], st[1]), p1 = pack_tiles(st[2], st[3]);
; #pragma unroll
;         for (int et = 0; et < 4; ++et) { OT[et] = __builtin_amdgcn_mfma_f32_16x16x32_bf16(vt_frag(vT, et, 0, r, q), p0, OT[et], 0, 0, 0);
;             OT[et] = __builtin_amdgcn_mfma_f32_16x16x32_bf16(vt_frag(vT, et, 1, r, q), p1, OT[et], 0, 0, 0); }
	v_mfma_f32_16x16x32_bf16 v[130:133], v[134:137], v[40:43], v[130:133]
	v_subrev_u32_e32 v137, 35, v91
	s_nop 6
	v_pk_mul_f32 v[46:47], v[44:45], v[132:133] op_sel_hi:[0,1]
	v_pk_mul_f32 v[44:45], v[44:45], v[130:131] op_sel_hi:[0,1]
	v_mfma_f32_16x16x32_bf16 v[130:133], v[0:3], v[34:37], 0
	v_mfma_f32_16x16x32_bf16 v[130:133], v[4:7], v[40:43], v[130:133]
	s_nop 7
	v_mul_f32_e32 v95, v89, v130
	v_add_u32_e32 v89, -1, v129
	v_subrev_u32_e32 v130, 50, v91
	v_cndmask_b32_e32 v89, v130, v89, vcc
	v_cvt_f32_u32_e32 v89, v89
	v_cmp_gt_u32_e32 vcc, v93, v112
	v_mul_f32_e32 v89, v85, v89
	v_exp_f32_e32 v89, v89
	s_nop 0
	v_mul_f32_e32 v130, v89, v131
	v_add_u32_e32 v89, -2, v129
	v_subrev_u32_e32 v131, 49, v91
	v_cndmask_b32_e32 v89, v131, v89, vcc
	v_cvt_f32_u32_e32 v89, v89
	v_cmp_gt_u32_e32 vcc, v93, v113
	v_cvt_pk_bf16_f32 v130, v95, v130
	v_mul_f32_e32 v89, v85, v89
	v_exp_f32_e32 v89, v89
	s_nop 0
	v_mul_f32_e32 v131, v89, v132
	v_add_u32_e32 v89, -3, v129
	v_subrev_u32_e32 v132, 48, v91
	v_cndmask_b32_e32 v89, v132, v89, vcc
	v_cvt_f32_u32_e32 v89, v89
	v_cmp_gt_u32_e32 vcc, v93, v114
	v_mul_f32_e32 v89, v85, v89
	v_exp_f32_e32 v89, v89
	s_nop 0
	v_mul_f32_e32 v136, v89, v133
	v_add_u32_e32 v89, -16, v129
	v_cndmask_b32_e32 v89, v137, v89, vcc
	v_cvt_f32_u32_e32 v89, v89
	v_mfma_f32_16x16x32_bf16 v[132:135], v[8:11], v[34:37], 0
	v_cmp_gt_u32_e32 vcc, v93, v115
	v_cvt_pk_bf16_f32 v131, v131, v136
	v_mul_f32_e32 v89, v85, v89
	v_mfma_f32_16x16x32_bf16 v[132:135], v[12:15], v[40:43], v[132:135]
	v_exp_f32_e32 v89, v89
	s_nop 6
	v_mul_f32_e32 v137, v89, v132
	v_subrev_u32_e32 v89, 17, v129
	v_subrev_u32_e32 v132, 34, v91
	v_cndmask_b32_e32 v89, v132, v89, vcc
	v_cvt_f32_u32_e32 v89, v89
	v_cmp_gt_u32_e32 vcc, v93, v116
	v_subrev_u32_e32 v132, 33, v91
	v_mul_f32_e32 v89, v85, v89
	v_exp_f32_e32 v89, v89
	s_nop 0
	v_mul_f32_e32 v138, v89, v133
	v_subrev_u32_e32 v89, 18, v129
	v_cndmask_b32_e32 v89, v132, v89, vcc
	v_cvt_f32_u32_e32 v89, v89
	v_cmp_gt_u32_e32 vcc, v93, v117
	v_subrev_u32_e32 v132, 32, v91
	v_mul_f32_e32 v89, v85, v89
	v_exp_f32_e32 v89, v89
	s_nop 0
	v_mul_f32_e32 v139, v89, v134
	v_subrev_u32_e32 v89, 19, v129
	v_cndmask_b32_e32 v89, v132, v89, vcc
	v_cvt_f32_u32_e32 v89, v89
	v_cmp_gt_u32_e32 vcc, v93, v118
	v_mul_f32_e32 v89, v85, v89
	v_exp_f32_e32 v89, v89
	s_nop 0
	v_mul_f32_e32 v140, v89, v135
	v_subrev_u32_e32 v89, 32, v129
	v_cndmask_b32_e32 v89, v141, v89, vcc
	v_cvt_f32_u32_e32 v89, v89
	v_mfma_f32_16x16x32_bf16 v[132:135], v[16:19], v[34:37], 0
	v_cmp_gt_u32_e32 vcc, v93, v119
	v_mul_f32_e32 v89, v85, v89
	v_mfma_f32_16x16x32_bf16 v[132:135], v[20:23], v[40:43], v[132:135]
	v_exp_f32_e32 v89, v89
	v_mfma_f32_16x16x32_bf16 v[34:37], v[24:27], v[34:37], 0
	v_mfma_f32_16x16x32_bf16 v[34:37], v[28:31], v[40:43], v[34:37]
	s_nop 4
	v_mul_f32_e32 v141, v89, v132
	v_subrev_u32_e32 v89, 33, v129
	v_subrev_u32_e32 v132, 18, v91
	v_cndmask_b32_e32 v89, v132, v89, vcc
	v_cvt_f32_u32_e32 v89, v89
	v_cmp_gt_u32_e32 vcc, v93, v120
	v_subrev_u32_e32 v132, 17, v91
	v_subrev_u32_e32 v40, 48, v129
	v_mul_f32_e32 v89, v85, v89
	v_exp_f32_e32 v89, v89
	v_add_u32_e32 v41, -3, v91
	v_mul_f32_e32 v142, v89, v133
	v_subrev_u32_e32 v89, 34, v129
	v_cndmask_b32_e32 v89, v132, v89, vcc
	v_cvt_f32_u32_e32 v89, v89
	v_cmp_gt_u32_e32 vcc, v93, v121
	v_subrev_u32_e32 v132, 35, v129
	v_cvt_pk_bf16_f32 v133, v139, v140
	v_mul_f32_e32 v89, v85, v89
	v_exp_f32_e32 v89, v89
	s_nop 0
	v_mul_f32_e32 v143, v89, v134
	v_add_u32_e32 v89, -16, v91
	v_cndmask_b32_e32 v132, v89, v132, vcc
	v_cmp_gt_u32_e32 vcc, v93, v122
	v_cvt_f32_u32_e32 v132, v132
	v_cvt_pk_bf16_f32 v134, v141, v142
	v_mul_f32_e32 v132, v85, v132
	v_cndmask_b32_e32 v40, v41, v40, vcc
	v_cvt_f32_u32_e32 v40, v40
	v_cmp_gt_u32_e32 vcc, v93, v123
	v_add_u32_e32 v41, -2, v91
	v_exp_f32_e32 v132, v132
	v_mul_f32_e32 v40, v85, v40
	v_exp_f32_e32 v40, v40
	v_mul_f32_e32 v135, v132, v135
	v_cvt_pk_bf16_f32 v132, v137, v138
	v_mul_f32_e32 v34, v40, v34
	v_subrev_u32_e32 v40, 49, v129
	v_cndmask_b32_e32 v40, v41, v40, vcc
	v_cvt_f32_u32_e32 v40, v40
	v_cmp_gt_u32_e32 vcc, v93, v124
	v_add_u32_e32 v41, -1, v91
	v_cvt_pk_bf16_f32 v135, v143, v135
	v_mul_f32_e32 v40, v85, v40
	v_exp_f32_e32 v40, v40
	s_nop 0
	v_mul_f32_e32 v35, v40, v35
	v_subrev_u32_e32 v40, 50, v129
	v_cndmask_b32_e32 v40, v41, v40, vcc
	v_cvt_f32_u32_e32 v40, v40
	v_cmp_gt_u32_e32 vcc, v93, v125
	v_cvt_pk_bf16_f32 v136, v34, v35
	v_mul_f32_e32 v40, v85, v40
	v_exp_f32_e32 v40, v40
	s_nop 0
	v_mul_f32_e32 v36, v40, v36
	v_subrev_u32_e32 v40, 51, v129
	v_cndmask_b32_e32 v40, v91, v40, vcc
	v_cvt_f32_u32_e32 v40, v40
	v_mul_f32_e32 v40, v85, v40
	v_exp_f32_e32 v40, v40
	s_nop 0
	v_mul_f32_e32 v37, v40, v37
	v_add_u32_e32 v40, v73, v62
	v_cvt_pk_bf16_f32 v137, v36, v37
	ds_read2_b64 v[34:37], v40 offset1:4
	ds_read2_b64 v[40:43], v40 offset0:8 offset1:12
	s_waitcnt lgkmcnt(1)
	v_mfma_f32_16x16x32_bf16 v[34:37], v[34:37], v[130:133], v[56:59]
	s_nop 2
	v_add_u32_e32 v56, v105, v62
	s_waitcnt lgkmcnt(0)
	v_mfma_f32_16x16x32_bf16 v[40:43], v[40:43], v[134:137], v[34:37]
	s_nop 2
	ds_read2_b64 v[34:37], v56 offset1:4
	s_waitcnt lgkmcnt(0)
	v_mfma_f32_16x16x32_bf16 v[34:37], v[34:37], v[130:133], v[52:55]
	s_nop 2
	ds_read2_b64 v[52:55], v56 offset0:8 offset1:12
	v_add_u32_e32 v56, v107, v62
	s_waitcnt lgkmcnt(0)
	v_mfma_f32_16x16x32_bf16 v[34:37], v[52:55], v[134:137], v[34:37]
	ds_read2_b64 v[52:55], v56 offset1:4
	s_waitcnt lgkmcnt(0)
	v_mfma_f32_16x16x32_bf16 v[48:51], v[52:55], v[130:133], v[48:51]
	ds_read2_b64 v[52:55], v56 offset0:8 offset1:12
	s_waitcnt lgkmcnt(0)
; __device__ __forceinline__ float sx(float v, int m, int lane) { return __builtin_bit_cast(float, __builtin_amdgcn_ds_bpermute((lane ^ m) << 2, __builtin_bit_cast(int, v))); }
; __device__ __forceinline__ void retout_item(const bf16_t* hbuf, const float* rot, const float* kvbuf, const float* normg, bf16_t* mixed, LAS bf16_t* vT, int item, int lane) {
;     ...
;         float s = 0.f;
; #pragma unroll
;         for (int et = 0; et < 4; ++et) s += (OT[et][0] + OT[et][1]) + (OT[et][2] + OT[et][3]);
;         s += sx(s, 16, lane); s += sx(s, 32, lane);
;         const float mu = s * (1.0f / 64.0f); float v = 0.f;
; #pragma unroll
;         for (int et = 0; et < 4; ++et)
; #pragma unroll
;             for (int j = 0; j < 4; ++j) { const float d = OT[et][j] - mu; v += d * d; }
;         v += sx(v, 16, lane); v += sx(v, 32, lane);
;         const float rstd = rsqrtf(v * (1.0f / 64.0f) + LN_EPS);
; #pragma unroll
;         for (int et = 0; et < 4; ++et) { const int e = 16 * et + 4 * q;
;             const u32x2 gw = *(const u32x2*)(hbuf + (t0 + c) * INWP + C_RG + h * 64 + e); const f32x4 ng = *(const f32x4*)(normg + h * 64 + e);
	v_mfma_f32_16x16x32_bf16 v[50:53], v[52:55], v[134:137], v[48:51]
	s_nop 4
	v_add_u32_e32 v48, v109, v62
	ds_read2_b64 v[54:57], v48 offset1:4
	v_mov_b32_e32 v49, v37
	s_waitcnt lgkmcnt(0)
	v_mfma_f32_16x16x32_bf16 v[44:47], v[54:57], v[130:133], v[44:47]
	ds_read2_b64 v[54:57], v48 offset0:8 offset1:12
	v_mov_b32_e32 v48, v34
	s_waitcnt lgkmcnt(0)
	v_mfma_f32_16x16x32_bf16 v[130:133], v[54:57], v[134:137], v[44:47]
	s_nop 3
	v_mov_b32_e32 v44, v41
	v_mov_b32_e32 v45, v42
	v_mov_b32_e32 v46, v40
	v_mov_b32_e32 v47, v43
	v_pk_add_f32 v[44:45], v[44:45], v[46:47]
	v_mov_b32_e32 v46, v35
	v_mov_b32_e32 v47, v36
	v_pk_add_f32 v[46:47], v[46:47], v[48:49]
	v_add_f32_e32 v44, v44, v45
	v_pk_add_f32 v[46:47], v[46:47], v[46:47] op_sel:[0,1] op_sel_hi:[1,0]
	v_add_f32_e32 v44, 0, v44
	v_add_f32_e32 v48, v50, v51
	v_add_f32_e32 v54, v52, v53
	v_mov_b32_e32 v45, v130
	v_mov_b32_e32 v47, v131
	v_mov_b32_e32 v49, v132
	v_mov_b32_e32 v55, v133
	v_pk_add_f32 v[44:45], v[44:45], v[46:47]
	v_pk_add_f32 v[46:47], v[48:49], v[54:55]
	s_nop 0
	v_pk_add_f32 v[44:45], v[44:45], v[46:47]
	s_nop 0
	v_add_f32_e32 v44, v44, v45
	ds_bpermute_b32 v45, v69, v44
	s_waitcnt lgkmcnt(0)
	v_add_f32_e32 v44, v44, v45
	ds_bpermute_b32 v45, v71, v44
	s_waitcnt lgkmcnt(0)
	v_add_f32_e32 v45, v44, v45
	v_fmamk_f32 v59, v45, 0xbc800000, v41
	v_fmamk_f32 v55, v45, 0xbc800000, v40
	v_mul_f32_e32 v40, v59, v59
	v_fmac_f32_e32 v40, v55, v55
	v_fmamk_f32 v91, v45, 0xbc800000, v42
	v_fmac_f32_e32 v40, v91, v91
	v_fmac_f32_e32 v43, 0xbc800000, v45
	v_fmac_f32_e32 v40, v43, v43
	v_fmamk_f32 v58, v45, 0xbc800000, v34
	v_fmac_f32_e32 v40, v58, v58
	v_fmamk_f32 v57, v45, 0xbc800000, v35
	v_mul_f32_e32 v44, 0x3c800000, v45
	v_fmac_f32_e32 v40, v57, v57
	v_fmamk_f32 v36, v45, 0xbc800000, v36
	v_fmac_f32_e32 v40, v36, v36
	v_fmac_f32_e32 v37, 0xbc800000, v45
	v_pk_add_f32 v[50:51], v[50:51], v[44:45] op_sel_hi:[1,0] neg_lo:[0,1] neg_hi:[0,1]
	v_fmac_f32_e32 v40, v37, v37
	v_pk_mul_f32 v[34:35], v[50:51], v[50:51]
	v_pk_add_f32 v[48:49], v[52:53], v[44:45] op_sel_hi:[1,0] neg_lo:[0,1] neg_hi:[0,1]
	v_add_f32_e32 v34, v34, v40
	v_add_f32_e32 v40, v35, v34
	v_pk_mul_f32 v[34:35], v[48:49], v[48:49]
	v_pk_add_f32 v[46:47], v[130:131], v[44:45] op_sel_hi:[1,0] neg_lo:[0,1] neg_hi:[0,1]
	v_add_f32_e32 v34, v34, v40
	v_add_f32_e32 v40, v35, v34
	v_pk_mul_f32 v[34:35], v[46:47], v[46:47]
	v_pk_add_f32 v[44:45], v[132:133], v[44:45] op_sel_hi:[1,0] neg_lo:[0,1] neg_hi:[0,1]
	v_add_f32_e32 v34, v34, v40
	v_add_f32_e32 v40, v35, v34
	v_pk_mul_f32 v[34:35], v[44:45], v[44:45]
	v_lshl_add_u64 v[52:53], v[98:99], 0, s[36:37]
	global_load_dwordx2 v[144:145], v[52:53], off offset:-64
	global_load_dwordx4 v[152:155], v[96:97], off
	global_load_dwordx2 v[146:147], v[52:53], off offset:-32
	global_load_dwordx4 v[156:159], v[96:97], off offset:64
	global_load_dwordx2 v[148:149], v[52:53], off
	global_load_dwordx4 v[160:163], v[96:97], off offset:128
	global_load_dwordx2 v[150:151], v[52:53], off offset:32
	global_load_dwordx4 v[172:175], v[96:97], off offset:192
	v_add_f32_e32 v34, v34, v40
	v_add_f32_e32 v34, v35, v34
	ds_bpermute_b32 v35, v69, v34
	v_lshl_add_u64 v[98:99], v[98:99], 0, s[10:11]
	s_waitcnt lgkmcnt(0)
	v_add_f32_e32 v34, v34, v35
	ds_bpermute_b32 v35, v71, v34
	s_waitcnt lgkmcnt(0)
	v_add_f32_e32 v34, v34, v35
	v_fmamk_f32 v34, v34, 0x3c800000, v206
	v_cmp_gt_f32_e32 vcc, s33, v34
	v_mul_f32_e32 v35, 0x4b800000, v34
	s_nop 0
	v_cndmask_b32_e32 v34, v34, v35, vcc
	v_rsq_f32_e32 v34, v34
	s_nop 0
	v_mul_f32_e32 v35, 0x45800000, v34
	v_cndmask_b32_e32 v56, v34, v35, vcc
	v_mul_f32_e32 v41, v55, v56
	v_mul_f32_e32 v55, v91, v56
	v_mul_f32_e32 v43, v43, v56
	v_mov_b32_e32 v91, v89
	s_waitcnt vmcnt(0)
; __device__ __forceinline__ unsigned pk2(float lo, float hi) { unsigned r; asm("v_cvt_pk_bf16_f32 %0, %1, %2" : "=v"(r) : "v"(lo), "v"(hi)); return r; }
; __device__ __forceinline__ float bflo(unsigned u) { return __uint_as_float(u << 16); }
; __device__ __forceinline__ float bfhi(unsigned u) { return __uint_as_float(u & 0xffff0000u); }
; __device__ __forceinline__ float sl(float v, int src) { return __builtin_bit_cast(float, __builtin_amdgcn_ds_bpermute(src << 2, __builtin_bit_cast(int, v))); }
; __device__ __forceinline__ void retout_item(const bf16_t* hbuf, const float* rot, const float* kvbuf, const float* normg, bf16_t* mixed, LAS bf16_t* vT, int item, int lane) {
;     ...
;         for (int et = 0; et < 4; ++et) { const int e = 16 * et + 4 * q;
;             const u32x2 gw = *(const u32x2*)(hbuf + (t0 + c) * INWP + C_RG + h * 64 + e); const f32x4 ng = *(const f32x4*)(normg + h * 64 + e);
;             float gt[4] = {bflo(gw.x), bfhi(gw.x), bflo(gw.y), bfhi(gw.y)}, o[4];
; #pragma unroll
;             for (int j = 0; j < 4; ++j) { const float sl = gt[j] * __builtin_amdgcn_rcpf(1.0f + __expf(-gt[j])); o[j] = (OT[et][j] - mu) * rstd * ng[j] * sl; }
;             u32x2 w; w.x = pk2(o[0], o[1]); w.y = pk2(o[2], o[3]);
;             *(u32x2*)(mixed + (t0 + c) * 1024 + M_RET + h * 64 + e) = w; }
;     }
; __device__ __forceinline__ void run_phase(const Args& a, const int ph, LAS unsigned char* lds, const int tid, const int rpt) {
;     ...
;                 for (int it = gw; it < 12 * NCHUNK; it += NGW) retout_item(hbuf, rot, (const float*)(ws + WS_RPREV), a.in[5] + l * 384, mixed, vT, it, lane);
	v_mov_b32_e32 v34, v144
	v_mov_b32_e32 v35, v145
	v_lshlrev_b32_e32 v40, 16, v34
	v_lshlrev_b32_e32 v54, 16, v35
	v_and_b32_e32 v42, 0xffff0000, v35
	v_mul_f32_e32 v35, 0xbfb8aa3b, v40
	v_exp_f32_e32 v35, v35
	v_and_b32_e32 v34, 0xffff0000, v34
	v_mov_b32_e32 v130, v152
	v_mov_b32_e32 v131, v153
	v_mov_b32_e32 v132, v154
	v_mov_b32_e32 v133, v155
	v_mov_b32_e32 v135, v130
	v_add_f32_e32 v35, 1.0, v35
	v_rcp_f32_e32 v134, v35
	v_mul_f32_e32 v35, 0xbfb8aa3b, v34
	v_exp_f32_e32 v35, v35
	v_pk_mul_f32 v[40:41], v[134:135], v[40:41]
	s_nop 0
	v_mul_f32_e32 v40, v40, v41
	v_add_f32_e32 v35, 1.0, v35
	v_rcp_f32_e32 v130, v35
	v_mul_f32_e32 v35, v59, v56
	v_mul_f32_e32 v135, v36, v56
	v_pk_mul_f32 v[34:35], v[130:131], v[34:35]
	s_nop 0
	v_mul_f32_e32 v41, v34, v35
	v_mul_f32_e32 v34, 0xbfb8aa3b, v54
	v_exp_f32_e32 v34, v34
	v_mov_b32_e32 v35, v132
	v_mul_f32_e32 v131, v58, v56
	v_add_f32_e32 v34, 1.0, v34
	v_rcp_f32_e32 v34, v34
	s_nop 0
	v_pk_mul_f32 v[34:35], v[34:35], v[54:55]
	s_nop 0
	v_mul_f32_e32 v54, v34, v35
	v_mul_f32_e32 v34, 0xbfb8aa3b, v42
	v_exp_f32_e32 v34, v34
	s_nop 0
	v_add_f32_e32 v34, 1.0, v34
	v_rcp_f32_e32 v132, v34
	s_nop 0
	v_pk_mul_f32 v[34:35], v[132:133], v[42:43]
	s_nop 0
	v_mul_f32_e32 v35, v34, v35
	v_cvt_pk_bf16_f32 v35, v54, v35
	v_lshl_add_u64 v[54:55], v[102:103], 0, s[36:37]
	v_cvt_pk_bf16_f32 v34, v40, v41
	global_store_dwordx2 v[54:55], v[34:35], off offset:-64
	s_nop 0
	v_mul_f32_e32 v133, v57, v56
	v_lshl_add_u64 v[102:103], v[102:103], 0, s[20:21]
	v_mov_b32_e32 v34, v146
	v_mov_b32_e32 v35, v147
	v_lshlrev_b32_e32 v130, 16, v34
	v_and_b32_e32 v132, 0xffff0000, v34
	v_lshlrev_b32_e32 v134, 16, v35
	v_and_b32_e32 v34, 0xffff0000, v35
	v_mul_f32_e32 v35, 0xbfb8aa3b, v130
	v_exp_f32_e32 v35, v35
	v_mov_b32_e32 v40, v156
	v_mov_b32_e32 v41, v157
	v_mov_b32_e32 v42, v158
	v_mov_b32_e32 v43, v159
	v_mov_b32_e32 v137, v40
	v_add_f32_e32 v35, 1.0, v35
	v_rcp_f32_e32 v136, v35
	v_mul_f32_e32 v35, 0xbfb8aa3b, v132
	v_exp_f32_e32 v35, v35
	v_pk_mul_f32 v[58:59], v[136:137], v[130:131]
	s_nop 0
	v_mul_f32_e32 v58, v58, v59
	v_add_f32_e32 v35, 1.0, v35
	v_rcp_f32_e32 v40, v35
	v_mul_f32_e32 v35, 0xbfb8aa3b, v134
	v_exp_f32_e32 v35, v35
	v_mul_f32_e32 v59, v51, v56
	v_pk_mul_f32 v[40:41], v[40:41], v[132:133]
	v_mul_f32_e32 v131, v48, v56
	v_add_f32_e32 v35, 1.0, v35
	v_mul_f32_e32 v57, v40, v41
	v_rcp_f32_e32 v40, v35
	v_mul_f32_e32 v35, 0xbfb8aa3b, v34
	v_exp_f32_e32 v35, v35
	v_mov_b32_e32 v41, v42
	v_pk_mul_f32 v[40:41], v[40:41], v[134:135]
	v_mul_f32_e32 v51, v45, v56
	v_add_f32_e32 v35, 1.0, v35
	v_rcp_f32_e32 v42, v35
	v_mul_f32_e32 v35, v37, v56
	v_mul_f32_e32 v36, v40, v41
	v_pk_mul_f32 v[34:35], v[42:43], v[34:35]
	s_nop 0
	v_mul_f32_e32 v35, v34, v35
	v_cvt_pk_bf16_f32 v34, v58, v57
	v_cvt_pk_bf16_f32 v35, v36, v35
	global_store_dwordx2 v[54:55], v[34:35], off offset:-32
	s_nop 0
	v_mul_f32_e32 v43, v50, v56
	v_mov_b32_e32 v40, v148
	v_mov_b32_e32 v41, v149
	v_lshlrev_b32_e32 v42, 16, v40
	v_and_b32_e32 v58, 0xffff0000, v40
	v_lshlrev_b32_e32 v130, 16, v41
	v_and_b32_e32 v40, 0xffff0000, v41
	v_mul_f32_e32 v41, 0xbfb8aa3b, v42
	v_mov_b32_e32 v34, v160
	v_mov_b32_e32 v35, v161
	v_mov_b32_e32 v36, v162
	v_mov_b32_e32 v37, v163
	v_mov_b32_e32 v133, v34
	v_mul_f32_e32 v34, 0xbfb8aa3b, v58
	v_exp_f32_e32 v41, v41
	v_exp_f32_e32 v34, v34
	v_add_f32_e32 v41, 1.0, v41
	v_add_f32_e32 v34, 1.0, v34
	v_rcp_f32_e32 v132, v41
	v_rcp_f32_e32 v34, v34
	v_mul_f32_e32 v41, v49, v56
	v_mul_f32_e32 v49, v44, v56
	v_pk_mul_f32 v[42:43], v[132:133], v[42:43]
	v_pk_mul_f32 v[34:35], v[34:35], v[58:59]
	v_mul_f32_e32 v42, v42, v43
	v_mul_f32_e32 v43, v34, v35
	v_mul_f32_e32 v34, 0xbfb8aa3b, v130
	v_exp_f32_e32 v34, v34
	v_mov_b32_e32 v35, v36
	v_add_f32_e32 v34, 1.0, v34
	v_rcp_f32_e32 v34, v34
	s_nop 0
	v_pk_mul_f32 v[34:35], v[34:35], v[130:131]
	s_nop 0
	v_mul_f32_e32 v48, v34, v35
	v_mul_f32_e32 v34, 0xbfb8aa3b, v40
	v_exp_f32_e32 v34, v34
	s_nop 0
	v_add_f32_e32 v34, 1.0, v34
	v_rcp_f32_e32 v36, v34
	s_nop 0
	v_pk_mul_f32 v[34:35], v[36:37], v[40:41]
	s_nop 0
	v_mul_f32_e32 v35, v34, v35
	v_cvt_pk_bf16_f32 v34, v42, v43
	v_cvt_pk_bf16_f32 v35, v48, v35
	global_store_dwordx2 v[54:55], v[34:35], off
	s_nop 0
	v_mul_f32_e32 v43, v46, v56
	v_mov_b32_e32 v40, v150
	v_mov_b32_e32 v41, v151
	v_lshlrev_b32_e32 v42, 16, v40
	v_and_b32_e32 v40, 0xffff0000, v40
	v_mov_b32_e32 v34, v172
	v_mov_b32_e32 v35, v173
	v_mov_b32_e32 v36, v174
	v_mov_b32_e32 v37, v175
	v_mov_b32_e32 v53, v34
	v_mul_f32_e32 v34, 0xbfb8aa3b, v40
	v_exp_f32_e32 v34, v34
	v_lshlrev_b32_e32 v48, 16, v41
	v_and_b32_e32 v50, 0xffff0000, v41
	v_mul_f32_e32 v41, 0xbfb8aa3b, v42
	v_exp_f32_e32 v41, v41
	v_add_f32_e32 v34, 1.0, v34
	v_rcp_f32_e32 v34, v34
	v_add_f32_e32 v41, 1.0, v41
	v_rcp_f32_e32 v52, v41
	v_mul_f32_e32 v41, v47, v56
	v_pk_mul_f32 v[34:35], v[34:35], v[40:41]
	v_pk_mul_f32 v[42:43], v[52:53], v[42:43]
	v_mul_f32_e32 v40, v34, v35
	v_mul_f32_e32 v34, 0xbfb8aa3b, v48
	v_exp_f32_e32 v34, v34
	v_mov_b32_e32 v35, v36
	v_mul_f32_e32 v42, v42, v43
	v_add_f32_e32 v34, 1.0, v34
	v_rcp_f32_e32 v34, v34
	s_nop 0
	v_pk_mul_f32 v[34:35], v[34:35], v[48:49]
	s_nop 0
	v_mul_f32_e32 v41, v34, v35
	v_mul_f32_e32 v34, 0xbfb8aa3b, v50
	v_exp_f32_e32 v34, v34
	s_nop 0
	v_add_f32_e32 v34, 1.0, v34
	v_rcp_f32_e32 v36, v34
	s_nop 0
	v_pk_mul_f32 v[34:35], v[36:37], v[50:51]
	s_nop 0
	v_mul_f32_e32 v35, v34, v35
	v_cvt_pk_bf16_f32 v34, v42, v40
	v_cvt_pk_bf16_f32 v35, v41, v35
	global_store_dwordx2 v[54:55], v[34:35], off offset:32
	s_cbranch_scc1 .LBB0_176
	s_waitcnt lgkmcnt(0)
	s_cmpk_gt_i32 s0, 0x7ff
	s_cbranch_scc1 .LBB0_178
	v_readlane_b32 s98, v249, 52
	s_nop 0
	s_cmp_gt_u32 s98, 3
	s_cbranch_scc1 .LBB0_178
	v_readlane_b32 s99, v251, 12
	s_nop 0
	s_lshl_b32 s99, s99, 2
	s_add_i32 s0, s98, s99
	s_add_i32 s0, s0, 0x800
	s_branch .LBB0_175
